# P6 epilogue: first row group loads hoisted above the K-loop drain/barriers (on top of v23)
# speedup vs baseline: 1.0073x; 1.0073x over previous
;     __device__ __forceinline__ void fused(f32x4 (&acc)[2][2][4][2], const Unit& u, int wr, int wc, int fr, int fq, PG8_LAS unsigned char* lds, int wid, int lane) const {
;         const PG8_LAS float* S = (const PG8_LAS float*)(lds + 8192);
;         const int col0 = u.pn * BM + wc * 32 + 8 * fq;
; #pragma unroll
;         for (int bj = 0; bj < 2; ++bj) {
;             const f32x4 b0 = *(const f32x4*)(gb + col0 + bj * HALF), b1 = *(const f32x4*)(gb + col0 + bj * HALF + 4);
; #pragma unroll
;             for (int ai = 0; ai < 2; ++ai)
; #pragma unroll
;                 for (int m = 0; m < 4; ++m) { acc[ai][bj][m][0] += b0; acc[ai][bj][m][1] += b1; } }
; #pragma unroll
;         for (int ai = 0; ai < 2; ++ai)
; #pragma unroll
;             for (int m = 0; m < 4; ++m) { const size_t off = (size_t)(u.pm * BM + ai * HALF + wr * 64 + m * 16 + fr) * 1024 + col0;
; #pragma unroll
;                 for (int bj = 0; bj < 2; ++bj) {
;                     const u32x4 xw = *(const u32x4*)(x1b + off + bj * HALF);
;                     f32x4 x0, x1;
;                     x0[0] = __uint_as_float(xw.x << 16); x0[1] = __uint_as_float(xw.x & 0xffff0000u); x0[2] = __uint_as_float(xw.y << 16); x0[3] = __uint_as_float(xw.y & 0xffff0000u);
;                     x1[0] = __uint_as_float(xw.z << 16); x1[1] = __uint_as_float(xw.z & 0xffff0000u); x1[2] = __uint_as_float(xw.w << 16); x1[3] = __uint_as_float(xw.w & 0xffff0000u);
;                     const u32x4 pw = *(const u32x4*)(pp + off + bj * HALF);
;                     f32x4 p0, p1;
;                     p0[0] = __uint_as_float(pw.x << 16); p0[1] = __uint_as_float(pw.x & 0xffff0000u); p0[2] = __uint_as_float(pw.y << 16); p0[3] = __uint_as_float(pw.y & 0xffff0000u);
;                     p1[0] = __uint_as_float(pw.z << 16); p1[1] = __uint_as_float(pw.z & 0xffff0000u); p1[2] = __uint_as_float(pw.w << 16); p1[3] = __uint_as_float(pw.w & 0xffff0000u);
;                     f32x4 g0 = acc[ai][bj][m][0], g1 = acc[ai][bj][m][1];
; template <class Epi, class Sched, bool ALIGN_EPI = false, bool SP2 = false>
; __device__ __forceinline__ void gemm_phase(PG8_LAS unsigned char* lds, const Gemm g, const Sched& S, const Epi& E, int wid_in) {
;     ...
;     PG8_WAIT_V(0);
;     if constexpr (!ALIGN_EPI) { if (wr == 0) PG8_BAR; }
;     PG8_BAR;
;     if constexpr (Epi::AFTER_DRAIN) { E.fused(acc, cur, wr, wc, fr, fq, lds, wid, lane); S.done(cur); }
.LBB0_989:
	s_add_u32 s0, s96, 0xdc00000
	s_addc_u32 s1, s97, 0
	v_ashrrev_i32_e32 v128, 1, v150
	s_lshl_b32 s2, s5, 5
	s_lshl_b32 s3, s6, 8
	v_and_b32_e32 v130, -8, v128
	s_or_b32 s2, s3, s2
	v_add_u32_e32 v144, s2, v130
	v_mov_b32_e32 v128, s54
	v_mov_b32_e32 v129, s55
	v_ashrrev_i32_e32 v145, 31, v144
	v_lshl_add_u64 v[136:137], v[144:145], 2, v[128:129]
	global_load_dwordx4 v[132:135], v[136:137], off
	global_load_dwordx4 v[128:131], v[136:137], off offset:16
	global_load_dwordx4 v[140:143], v[136:137], off offset:512
	s_nop 0
	global_load_dwordx4 v[136:139], v[136:137], off offset:528
	s_lshl_b32 s16, s4, 8
	s_add_i32 s2, s16, s12
	v_or_b32_e32 v146, s2, v152
	v_ashrrev_i32_e32 v147, 31, v146
	v_lshlrev_b64 v[152:153], 10, v[146:147]
	v_lshl_add_u64 v[152:153], v[152:153], 0, v[144:145]
	v_lshlrev_b64 v[156:157], 1, v[152:153]
	v_lshl_add_u64 v[160:161], s[8:9], 0, v[156:157]
	global_load_dwordx4 v[152:155], v[160:161], off
	v_lshl_add_u64 v[164:165], s[0:1], 0, v[156:157]
	global_load_dwordx4 v[156:159], v[164:165], off
	s_nop 0
	global_load_dwordx4 v[160:163], v[160:161], off offset:256
	s_nop 0
	global_load_dwordx4 v[164:167], v[164:165], off offset:256
	s_waitcnt vmcnt(0)
	s_cmpk_gt_u32 s71, 0xff
	s_cbranch_scc1 .LBB0_991
	s_barrier
.LBB0_991:
	s_barrier
	s_waitcnt vmcnt(0)
	v_pk_add_f32 v[60:61], v[60:61], v[132:133]
	v_pk_add_f32 v[56:57], v[56:57], v[128:129]
	v_mul_f32_e32 v60, 0xbfb8aa3b, v60
	v_mul_f32_e32 v56, 0xbfb8aa3b, v56
	v_exp_f32_e32 v147, v60
	v_exp_f32_e32 v172, v56
	v_pk_add_f32 v[36:37], v[36:37], v[140:141]
	v_pk_add_f32 v[32:33], v[32:33], v[136:137]
	v_add_f32_e32 v147, 1.0, v147
	v_mul_f32_e32 v36, 0xbfb8aa3b, v36
	v_mul_f32_e32 v32, 0xbfb8aa3b, v32
	v_add_f32_e32 v179, 1.0, v172
	v_rcp_f32_e32 v172, v147
	v_exp_f32_e32 v36, v36
	v_exp_f32_e32 v147, v32
	v_mul_f32_e32 v37, 0xbfb8aa3b, v37
	v_mul_f32_e32 v33, 0xbfb8aa3b, v33
	v_add_f32_e32 v32, 1.0, v36
	v_add_f32_e32 v36, 1.0, v147
	v_exp_f32_e32 v37, v37
	v_exp_f32_e32 v147, v33
	v_mul_f32_e32 v61, 0xbfb8aa3b, v61
	v_pk_add_f32 v[38:39], v[38:39], v[142:143]
	v_pk_add_f32 v[34:35], v[34:35], v[138:139]
	v_exp_f32_e32 v173, v61
	v_mul_f32_e32 v38, 0xbfb8aa3b, v38
	v_mul_f32_e32 v34, 0xbfb8aa3b, v34
	v_add_f32_e32 v33, 1.0, v37
	v_add_f32_e32 v37, 1.0, v147
	v_exp_f32_e32 v38, v38
	v_exp_f32_e32 v147, v34
	v_pk_add_f32 v[62:63], v[62:63], v[134:135]
	v_pk_add_f32 v[58:59], v[58:59], v[130:131]
	v_mul_f32_e32 v57, 0xbfb8aa3b, v57
	v_mul_f32_e32 v62, 0xbfb8aa3b, v62
	v_mul_f32_e32 v58, 0xbfb8aa3b, v58
	v_mul_f32_e32 v63, 0xbfb8aa3b, v63
	v_mul_f32_e32 v59, 0xbfb8aa3b, v59
	v_exp_f32_e32 v174, v57
	v_add_f32_e32 v173, 1.0, v173
	v_exp_f32_e32 v175, v62
	v_exp_f32_e32 v176, v58
	v_exp_f32_e32 v177, v63
	v_exp_f32_e32 v178, v59
	v_rcp_f32_e32 v173, v173
	v_mul_f32_e32 v39, 0xbfb8aa3b, v39
	v_mul_f32_e32 v35, 0xbfb8aa3b, v35
	v_rcp_f32_e32 v32, v32
	v_rcp_f32_e32 v33, v33
	v_add_f32_e32 v34, 1.0, v38
	v_add_f32_e32 v38, 1.0, v147
	v_exp_f32_e32 v39, v39
	v_exp_f32_e32 v147, v35
	v_lshlrev_b32_e32 v56, 16, v152
	v_and_b32_e32 v57, 0xffff0000, v152
	v_lshlrev_b32_e32 v58, 16, v153
	v_and_b32_e32 v59, 0xffff0000, v153
	v_lshlrev_b32_e32 v152, 16, v156
	v_and_b32_e32 v153, 0xffff0000, v156
	v_add_f32_e32 v180, 1.0, v174
	v_lshlrev_b32_e32 v168, 16, v160
	v_and_b32_e32 v169, 0xffff0000, v160
	v_add_f32_e32 v181, 1.0, v175
	v_add_f32_e32 v182, 1.0, v176
	v_add_f32_e32 v177, 1.0, v177
	v_add_f32_e32 v183, 1.0, v178
	v_rcp_f32_e32 v174, v179
	v_rcp_f32_e32 v175, v180
	v_pk_fma_f32 v[56:57], v[172:173], v[152:153], v[56:57]
	v_lshlrev_b32_e32 v152, 16, v164
	v_and_b32_e32 v153, 0xffff0000, v164
	v_rcp_f32_e32 v176, v181
	v_rcp_f32_e32 v177, v177
	v_rcp_f32_e32 v178, v182
	v_rcp_f32_e32 v179, v183
	v_rcp_f32_e32 v36, v36
	v_rcp_f32_e32 v37, v37
	v_add_f32_e32 v35, 1.0, v39
	v_add_f32_e32 v39, 1.0, v147
	v_pk_fma_f32 v[32:33], v[32:33], v[152:153], v[168:169]
	v_or_b32_e32 v152, 16, v146
	v_rcp_f32_e32 v34, v34
	v_rcp_f32_e32 v38, v38
	v_rcp_f32_e32 v35, v35
	v_rcp_f32_e32 v39, v39
	v_ashrrev_i32_e32 v153, 31, v152
	v_lshlrev_b32_e32 v60, 16, v154
	v_and_b32_e32 v61, 0xffff0000, v154
	v_lshlrev_b32_e32 v62, 16, v155
	v_and_b32_e32 v63, 0xffff0000, v155
	v_lshlrev_b32_e32 v154, 16, v157
	v_and_b32_e32 v155, 0xffff0000, v157
	v_lshlrev_b32_e32 v156, 16, v158
	v_and_b32_e32 v157, 0xffff0000, v158
	v_lshlrev_b64 v[152:153], 10, v[152:153]
	v_lshlrev_b32_e32 v158, 16, v159
	v_and_b32_e32 v159, 0xffff0000, v159
	v_lshlrev_b32_e32 v170, 16, v162
	v_and_b32_e32 v171, 0xffff0000, v162
	v_pk_fma_f32 v[60:61], v[174:175], v[156:157], v[60:61]
	v_lshlrev_b32_e32 v156, 16, v166
	v_and_b32_e32 v157, 0xffff0000, v166
	v_lshl_add_u64 v[152:153], v[152:153], 0, v[144:145]
	v_lshlrev_b32_e32 v160, 16, v161
	v_and_b32_e32 v161, 0xffff0000, v161
	v_lshlrev_b32_e32 v162, 16, v163
	v_and_b32_e32 v163, 0xffff0000, v163
	v_pk_fma_f32 v[58:59], v[176:177], v[154:155], v[58:59]
	v_pk_fma_f32 v[62:63], v[178:179], v[158:159], v[62:63]
	v_lshlrev_b32_e32 v154, 16, v165
	v_and_b32_e32 v155, 0xffff0000, v165
	v_lshlrev_b32_e32 v158, 16, v167
	v_and_b32_e32 v159, 0xffff0000, v167
	v_pk_fma_f32 v[36:37], v[36:37], v[156:157], v[170:171]
	v_lshlrev_b64 v[156:157], 1, v[152:153]
	v_pk_fma_f32 v[34:35], v[34:35], v[154:155], v[160:161]
	v_pk_fma_f32 v[38:39], v[38:39], v[158:159], v[162:163]
	v_lshl_add_u64 v[160:161], s[8:9], 0, v[156:157]
	global_load_dwordx4 v[152:155], v[160:161], off
	v_lshl_add_u64 v[164:165], s[0:1], 0, v[156:157]
	global_load_dwordx4 v[156:159], v[164:165], off
	s_nop 0
	global_load_dwordx4 v[160:163], v[160:161], off offset:256
	s_nop 0
	global_load_dwordx4 v[164:167], v[164:165], off offset:256
;     __device__ __forceinline__ void fused(f32x4 (&acc)[2][2][4][2], const Unit& u, int wr, int wc, int fr, int fq, PG8_LAS unsigned char* lds, int wid, int lane) const {
;     ...
;         for (int ai = 0; ai < 2; ++ai)
; #pragma unroll
;             for (int m = 0; m < 4; ++m) { const size_t off = (size_t)(u.pm * BM + ai * HALF + wr * 64 + m * 16 + fr) * 1024 + col0;
; #pragma unroll
;                 for (int bj = 0; bj < 2; ++bj) {
;                     const u32x4 xw = *(const u32x4*)(x1b + off + bj * HALF);
;                     f32x4 x0, x1;
;                     x0[0] = __uint_as_float(xw.x << 16); x0[1] = __uint_as_float(xw.x & 0xffff0000u); x0[2] = __uint_as_float(xw.y << 16); x0[3] = __uint_as_float(xw.y & 0xffff0000u);
;                     x1[0] = __uint_as_float(xw.z << 16); x1[1] = __uint_as_float(xw.z & 0xffff0000u); x1[2] = __uint_as_float(xw.w << 16); x1[3] = __uint_as_float(xw.w & 0xffff0000u);
;                     const u32x4 pw = *(const u32x4*)(pp + off + bj * HALF);
;                     f32x4 p0, p1;
;                     p0[0] = __uint_as_float(pw.x << 16); p0[1] = __uint_as_float(pw.x & 0xffff0000u); p0[2] = __uint_as_float(pw.y << 16); p0[3] = __uint_as_float(pw.y & 0xffff0000u);
;                     p1[0] = __uint_as_float(pw.z << 16); p1[1] = __uint_as_float(pw.z & 0xffff0000u); p1[2] = __uint_as_float(pw.w << 16); p1[3] = __uint_as_float(pw.w & 0xffff0000u);
;                     f32x4 g0 = acc[ai][bj][m][0], g1 = acc[ai][bj][m][1];
; #pragma unroll
;                     for (int e = 0; e < 4; ++e) { g0[e] = __builtin_amdgcn_rcpf(1.f + __expf(-g0[e])); g1[e] = __builtin_amdgcn_rcpf(1.f + __expf(-g1[e])); }
;                     acc[ai][bj][m][0] = x0 + g0 * p0; acc[ai][bj][m][1] = x1 + g1 * p1; }
	v_pk_add_f32 v[88:89], v[88:89], v[132:133]
	v_pk_add_f32 v[84:85], v[84:85], v[128:129]
	v_mul_f32_e32 v88, 0xbfb8aa3b, v88
	v_mul_f32_e32 v84, 0xbfb8aa3b, v84
	v_exp_f32_e32 v88, v88
	v_exp_f32_e32 v147, v84
	v_mul_f32_e32 v89, 0xbfb8aa3b, v89
	v_mul_f32_e32 v85, 0xbfb8aa3b, v85
	v_add_f32_e32 v84, 1.0, v88
	v_add_f32_e32 v88, 1.0, v147
	v_exp_f32_e32 v89, v89
	v_exp_f32_e32 v147, v85
	v_pk_add_f32 v[90:91], v[90:91], v[134:135]
	v_pk_add_f32 v[86:87], v[86:87], v[130:131]
	v_mul_f32_e32 v90, 0xbfb8aa3b, v90
	v_mul_f32_e32 v86, 0xbfb8aa3b, v86
	v_add_f32_e32 v85, 1.0, v89
	v_add_f32_e32 v89, 1.0, v147
	v_exp_f32_e32 v90, v90
	v_exp_f32_e32 v147, v86
	v_mul_f32_e32 v91, 0xbfb8aa3b, v91
	v_mul_f32_e32 v87, 0xbfb8aa3b, v87
	v_add_f32_e32 v86, 1.0, v90
	v_add_f32_e32 v90, 1.0, v147
	v_exp_f32_e32 v91, v91
	v_exp_f32_e32 v147, v87
	v_pk_add_f32 v[68:69], v[68:69], v[140:141]
	v_pk_add_f32 v[64:65], v[64:65], v[136:137]
	v_mul_f32_e32 v68, 0xbfb8aa3b, v68
	v_mul_f32_e32 v64, 0xbfb8aa3b, v64
	v_add_f32_e32 v87, 1.0, v91
	v_add_f32_e32 v91, 1.0, v147
	v_exp_f32_e32 v68, v68
	v_exp_f32_e32 v147, v64
	v_mul_f32_e32 v69, 0xbfb8aa3b, v69
	v_mul_f32_e32 v65, 0xbfb8aa3b, v65
	v_add_f32_e32 v64, 1.0, v68
	v_add_f32_e32 v68, 1.0, v147
	v_exp_f32_e32 v69, v69
	v_exp_f32_e32 v147, v65
	v_pk_add_f32 v[70:71], v[70:71], v[142:143]
	v_pk_add_f32 v[66:67], v[66:67], v[138:139]
	v_mul_f32_e32 v70, 0xbfb8aa3b, v70
	v_mul_f32_e32 v66, 0xbfb8aa3b, v66
	v_add_f32_e32 v65, 1.0, v69
	v_add_f32_e32 v69, 1.0, v147
	v_exp_f32_e32 v70, v70
	v_exp_f32_e32 v147, v66
	v_rcp_f32_e32 v86, v86
	v_rcp_f32_e32 v90, v90
	v_rcp_f32_e32 v87, v87
	v_rcp_f32_e32 v91, v91
	v_mul_f32_e32 v71, 0xbfb8aa3b, v71
	v_mul_f32_e32 v67, 0xbfb8aa3b, v67
	v_rcp_f32_e32 v64, v64
	v_rcp_f32_e32 v65, v65
	v_add_f32_e32 v66, 1.0, v70
	v_add_f32_e32 v70, 1.0, v147
	v_exp_f32_e32 v71, v71
	v_exp_f32_e32 v147, v67
	v_rcp_f32_e32 v68, v68
	v_rcp_f32_e32 v69, v69
	v_add_f32_e32 v67, 1.0, v71
	v_add_f32_e32 v71, 1.0, v147
	v_rcp_f32_e32 v84, v84
	v_rcp_f32_e32 v88, v88
	v_rcp_f32_e32 v85, v85
	v_rcp_f32_e32 v89, v89
	v_rcp_f32_e32 v66, v66
	v_rcp_f32_e32 v70, v70
	v_rcp_f32_e32 v67, v67
	v_rcp_f32_e32 v71, v71
	v_pk_add_f32 v[108:109], v[108:109], v[132:133]
	v_pk_add_f32 v[104:105], v[104:105], v[128:129]
	v_mul_f32_e32 v108, 0xbfb8aa3b, v108
	v_mul_f32_e32 v104, 0xbfb8aa3b, v104
	v_exp_f32_e32 v108, v108
	s_waitcnt vmcnt(3)
	v_lshlrev_b32_e32 v168, 16, v152
	v_and_b32_e32 v169, 0xffff0000, v152
	v_lshlrev_b32_e32 v152, 16, v153
	v_and_b32_e32 v153, 0xffff0000, v153
	v_lshlrev_b32_e32 v170, 16, v154
	v_and_b32_e32 v171, 0xffff0000, v154
	v_lshlrev_b32_e32 v154, 16, v155
	v_and_b32_e32 v155, 0xffff0000, v155
	s_waitcnt vmcnt(2)
	v_lshlrev_b32_e32 v172, 16, v156
	v_and_b32_e32 v173, 0xffff0000, v156
	v_lshlrev_b32_e32 v156, 16, v157
	v_and_b32_e32 v157, 0xffff0000, v157
	v_lshlrev_b32_e32 v174, 16, v158
	v_and_b32_e32 v175, 0xffff0000, v158
	v_lshlrev_b32_e32 v158, 16, v159
	v_and_b32_e32 v159, 0xffff0000, v159
	v_pk_fma_f32 v[86:87], v[86:87], v[156:157], v[152:153]
	v_pk_fma_f32 v[90:91], v[90:91], v[158:159], v[154:155]
	s_waitcnt vmcnt(1)
	v_lshlrev_b32_e32 v152, 16, v160
	v_and_b32_e32 v153, 0xffff0000, v160
	v_lshlrev_b32_e32 v154, 16, v161
	v_and_b32_e32 v155, 0xffff0000, v161
	s_waitcnt vmcnt(0)
	v_lshlrev_b32_e32 v160, 16, v164
	v_and_b32_e32 v161, 0xffff0000, v164
	v_pk_fma_f32 v[64:65], v[64:65], v[160:161], v[152:153]
	v_or_b32_e32 v152, 32, v146
	v_ashrrev_i32_e32 v153, 31, v152
	v_lshlrev_b64 v[152:153], 10, v[152:153]
	v_lshlrev_b32_e32 v156, 16, v162
	v_and_b32_e32 v157, 0xffff0000, v162
	v_lshlrev_b32_e32 v158, 16, v163
	v_and_b32_e32 v159, 0xffff0000, v163
	v_lshlrev_b32_e32 v162, 16, v165
	v_and_b32_e32 v163, 0xffff0000, v165
	v_lshlrev_b32_e32 v164, 16, v166
	v_and_b32_e32 v165, 0xffff0000, v166
	v_lshl_add_u64 v[152:153], v[152:153], 0, v[144:145]
	v_lshlrev_b32_e32 v166, 16, v167
	v_and_b32_e32 v167, 0xffff0000, v167
	v_pk_fma_f32 v[68:69], v[68:69], v[164:165], v[156:157]
	v_lshlrev_b64 v[156:157], 1, v[152:153]
	v_pk_fma_f32 v[84:85], v[84:85], v[172:173], v[168:169]
	v_pk_fma_f32 v[88:89], v[88:89], v[174:175], v[170:171]
	v_pk_fma_f32 v[66:67], v[66:67], v[162:163], v[154:155]
	v_pk_fma_f32 v[70:71], v[70:71], v[166:167], v[158:159]
	v_lshl_add_u64 v[160:161], s[8:9], 0, v[156:157]
	global_load_dwordx4 v[152:155], v[160:161], off
	v_lshl_add_u64 v[164:165], s[0:1], 0, v[156:157]
	global_load_dwordx4 v[156:159], v[164:165], off
	s_nop 0
	global_load_dwordx4 v[160:163], v[160:161], off offset:256
	s_nop 0
	global_load_dwordx4 v[164:167], v[164:165], off offset:256
	v_exp_f32_e32 v147, v104
	v_mul_f32_e32 v109, 0xbfb8aa3b, v109
	v_mul_f32_e32 v105, 0xbfb8aa3b, v105
	v_add_f32_e32 v104, 1.0, v108
	v_add_f32_e32 v108, 1.0, v147
	v_exp_f32_e32 v109, v109
	v_exp_f32_e32 v147, v105
	v_pk_add_f32 v[110:111], v[110:111], v[134:135]
	v_pk_add_f32 v[106:107], v[106:107], v[130:131]
	v_mul_f32_e32 v110, 0xbfb8aa3b, v110
	v_mul_f32_e32 v106, 0xbfb8aa3b, v106
	v_add_f32_e32 v105, 1.0, v109
	v_add_f32_e32 v109, 1.0, v147
	v_exp_f32_e32 v110, v110
	v_exp_f32_e32 v147, v106
	v_mul_f32_e32 v111, 0xbfb8aa3b, v111
	v_mul_f32_e32 v107, 0xbfb8aa3b, v107
	v_add_f32_e32 v106, 1.0, v110
	v_add_f32_e32 v110, 1.0, v147
	v_exp_f32_e32 v111, v111
	v_exp_f32_e32 v147, v107
	v_pk_add_f32 v[100:101], v[100:101], v[140:141]
	v_pk_add_f32 v[96:97], v[96:97], v[136:137]
	v_mul_f32_e32 v100, 0xbfb8aa3b, v100
	v_mul_f32_e32 v96, 0xbfb8aa3b, v96
	v_add_f32_e32 v107, 1.0, v111
	v_add_f32_e32 v111, 1.0, v147
	v_exp_f32_e32 v100, v100
	v_exp_f32_e32 v147, v96
	v_mul_f32_e32 v101, 0xbfb8aa3b, v101
	v_mul_f32_e32 v97, 0xbfb8aa3b, v97
;     __device__ __forceinline__ void fused(f32x4 (&acc)[2][2][4][2], const Unit& u, int wr, int wc, int fr, int fq, PG8_LAS unsigned char* lds, int wid, int lane) const {
;     ...
;         for (int ai = 0; ai < 2; ++ai)
; #pragma unroll
;             for (int m = 0; m < 4; ++m) { const size_t off = (size_t)(u.pm * BM + ai * HALF + wr * 64 + m * 16 + fr) * 1024 + col0;
; #pragma unroll
;                 for (int bj = 0; bj < 2; ++bj) {
;                     const u32x4 xw = *(const u32x4*)(x1b + off + bj * HALF);
;                     f32x4 x0, x1;
;                     x0[0] = __uint_as_float(xw.x << 16); x0[1] = __uint_as_float(xw.x & 0xffff0000u); x0[2] = __uint_as_float(xw.y << 16); x0[3] = __uint_as_float(xw.y & 0xffff0000u);
;                     x1[0] = __uint_as_float(xw.z << 16); x1[1] = __uint_as_float(xw.z & 0xffff0000u); x1[2] = __uint_as_float(xw.w << 16); x1[3] = __uint_as_float(xw.w & 0xffff0000u);
;                     const u32x4 pw = *(const u32x4*)(pp + off + bj * HALF);
;                     f32x4 p0, p1;
;                     p0[0] = __uint_as_float(pw.x << 16); p0[1] = __uint_as_float(pw.x & 0xffff0000u); p0[2] = __uint_as_float(pw.y << 16); p0[3] = __uint_as_float(pw.y & 0xffff0000u);
;                     p1[0] = __uint_as_float(pw.z << 16); p1[1] = __uint_as_float(pw.z & 0xffff0000u); p1[2] = __uint_as_float(pw.w << 16); p1[3] = __uint_as_float(pw.w & 0xffff0000u);
;                     f32x4 g0 = acc[ai][bj][m][0], g1 = acc[ai][bj][m][1];
; #pragma unroll
;                     for (int e = 0; e < 4; ++e) { g0[e] = __builtin_amdgcn_rcpf(1.f + __expf(-g0[e])); g1[e] = __builtin_amdgcn_rcpf(1.f + __expf(-g1[e])); }
;                     acc[ai][bj][m][0] = x0 + g0 * p0; acc[ai][bj][m][1] = x1 + g1 * p1; }
	v_add_f32_e32 v96, 1.0, v100
	v_add_f32_e32 v100, 1.0, v147
	v_exp_f32_e32 v101, v101
	v_exp_f32_e32 v147, v97
	v_pk_add_f32 v[102:103], v[102:103], v[142:143]
	v_pk_add_f32 v[98:99], v[98:99], v[138:139]
	v_mul_f32_e32 v102, 0xbfb8aa3b, v102
	v_mul_f32_e32 v98, 0xbfb8aa3b, v98
	v_add_f32_e32 v97, 1.0, v101
	v_add_f32_e32 v101, 1.0, v147
	v_exp_f32_e32 v102, v102
	v_exp_f32_e32 v147, v98
	v_rcp_f32_e32 v106, v106
	v_rcp_f32_e32 v110, v110
	v_rcp_f32_e32 v107, v107
	v_rcp_f32_e32 v111, v111
	v_mul_f32_e32 v103, 0xbfb8aa3b, v103
	v_mul_f32_e32 v99, 0xbfb8aa3b, v99
	v_rcp_f32_e32 v96, v96
	v_rcp_f32_e32 v97, v97
	v_add_f32_e32 v98, 1.0, v102
	v_add_f32_e32 v102, 1.0, v147
	v_exp_f32_e32 v103, v103
	v_exp_f32_e32 v147, v99
	v_rcp_f32_e32 v100, v100
	v_rcp_f32_e32 v101, v101
	v_add_f32_e32 v99, 1.0, v103
	v_add_f32_e32 v103, 1.0, v147
	v_rcp_f32_e32 v104, v104
	v_rcp_f32_e32 v108, v108
	v_rcp_f32_e32 v105, v105
	v_rcp_f32_e32 v109, v109
	v_rcp_f32_e32 v98, v98
	v_rcp_f32_e32 v102, v102
	v_rcp_f32_e32 v99, v99
	v_rcp_f32_e32 v103, v103
	v_pk_add_f32 v[124:125], v[124:125], v[132:133]
	v_pk_add_f32 v[120:121], v[120:121], v[128:129]
	v_mul_f32_e32 v124, 0xbfb8aa3b, v124
	v_mul_f32_e32 v120, 0xbfb8aa3b, v120
	v_exp_f32_e32 v124, v124
	v_exp_f32_e32 v147, v120
	v_mul_f32_e32 v121, 0xbfb8aa3b, v121
	v_mul_f32_e32 v125, 0xbfb8aa3b, v125
	v_add_f32_e32 v120, 1.0, v124
	v_add_f32_e32 v124, 1.0, v147
	s_waitcnt vmcnt(3)
	v_lshlrev_b32_e32 v168, 16, v152
	v_and_b32_e32 v169, 0xffff0000, v152
	v_lshlrev_b32_e32 v152, 16, v153
	v_and_b32_e32 v153, 0xffff0000, v153
	v_lshlrev_b32_e32 v170, 16, v154
	v_and_b32_e32 v171, 0xffff0000, v154
	v_lshlrev_b32_e32 v154, 16, v155
	v_and_b32_e32 v155, 0xffff0000, v155
	s_waitcnt vmcnt(2)
	v_lshlrev_b32_e32 v172, 16, v156
	v_and_b32_e32 v173, 0xffff0000, v156
	v_lshlrev_b32_e32 v156, 16, v157
	v_and_b32_e32 v157, 0xffff0000, v157
	v_lshlrev_b32_e32 v174, 16, v158
	v_and_b32_e32 v175, 0xffff0000, v158
	v_lshlrev_b32_e32 v158, 16, v159
	v_and_b32_e32 v159, 0xffff0000, v159
	v_pk_fma_f32 v[106:107], v[106:107], v[156:157], v[152:153]
	v_pk_fma_f32 v[110:111], v[110:111], v[158:159], v[154:155]
	s_waitcnt vmcnt(1)
	v_lshlrev_b32_e32 v152, 16, v160
	v_and_b32_e32 v153, 0xffff0000, v160
	v_lshlrev_b32_e32 v154, 16, v161
	v_and_b32_e32 v155, 0xffff0000, v161
	s_waitcnt vmcnt(0)
	v_lshlrev_b32_e32 v160, 16, v164
	v_and_b32_e32 v161, 0xffff0000, v164
	v_pk_fma_f32 v[96:97], v[96:97], v[160:161], v[152:153]
	v_or_b32_e32 v152, 48, v146
	v_ashrrev_i32_e32 v153, 31, v152
	v_lshlrev_b64 v[152:153], 10, v[152:153]
	v_lshlrev_b32_e32 v156, 16, v162
	v_and_b32_e32 v157, 0xffff0000, v162
	v_lshlrev_b32_e32 v158, 16, v163
	v_and_b32_e32 v159, 0xffff0000, v163
	v_lshlrev_b32_e32 v162, 16, v165
	v_and_b32_e32 v163, 0xffff0000, v165
	v_lshlrev_b32_e32 v164, 16, v166
	v_and_b32_e32 v165, 0xffff0000, v166
	v_lshl_add_u64 v[152:153], v[152:153], 0, v[144:145]
	v_lshlrev_b32_e32 v166, 16, v167
	v_and_b32_e32 v167, 0xffff0000, v167
	v_pk_fma_f32 v[100:101], v[100:101], v[164:165], v[156:157]
	v_lshlrev_b64 v[156:157], 1, v[152:153]
	v_pk_fma_f32 v[104:105], v[104:105], v[172:173], v[168:169]
	v_pk_fma_f32 v[108:109], v[108:109], v[174:175], v[170:171]
	v_pk_fma_f32 v[98:99], v[98:99], v[162:163], v[154:155]
	v_pk_fma_f32 v[102:103], v[102:103], v[166:167], v[158:159]
	v_lshl_add_u64 v[160:161], s[8:9], 0, v[156:157]
	global_load_dwordx4 v[152:155], v[160:161], off
	v_lshl_add_u64 v[164:165], s[0:1], 0, v[156:157]
	global_load_dwordx4 v[156:159], v[164:165], off
	s_nop 0
	global_load_dwordx4 v[160:163], v[160:161], off offset:256
	s_nop 0
	global_load_dwordx4 v[164:167], v[164:165], off offset:256
	v_exp_f32_e32 v147, v121
	v_exp_f32_e32 v125, v125
	v_pk_add_f32 v[116:117], v[116:117], v[140:141]
	v_pk_add_f32 v[112:113], v[112:113], v[136:137]
	v_mul_f32_e32 v116, 0xbfb8aa3b, v116
	v_mul_f32_e32 v112, 0xbfb8aa3b, v112
	v_pk_add_f32 v[126:127], v[126:127], v[134:135]
	v_rcp_f32_e32 v176, v124
	v_add_f32_e32 v124, 1.0, v147
	v_exp_f32_e32 v116, v116
	v_exp_f32_e32 v147, v112
	v_pk_add_f32 v[122:123], v[122:123], v[130:131]
	v_add_f32_e32 v121, 1.0, v125
	v_mul_f32_e32 v125, 0xbfb8aa3b, v126
	v_exp_f32_e32 v125, v125
	v_mul_f32_e32 v122, 0xbfb8aa3b, v122
	v_exp_f32_e32 v126, v122
	v_mul_f32_e32 v117, 0xbfb8aa3b, v117
	v_mul_f32_e32 v113, 0xbfb8aa3b, v113
	v_add_f32_e32 v112, 1.0, v116
	v_add_f32_e32 v116, 1.0, v147
	v_exp_f32_e32 v117, v117
	v_exp_f32_e32 v147, v113
	v_pk_add_f32 v[118:119], v[118:119], v[142:143]
	v_pk_add_f32 v[114:115], v[114:115], v[138:139]
	v_add_f32_e32 v122, 1.0, v125
	v_mul_f32_e32 v125, 0xbfb8aa3b, v127
	v_mul_f32_e32 v123, 0xbfb8aa3b, v123
	v_rcp_f32_e32 v177, v124
	v_add_f32_e32 v124, 1.0, v126
	v_exp_f32_e32 v125, v125
	v_exp_f32_e32 v126, v123
	v_mul_f32_e32 v118, 0xbfb8aa3b, v118
	v_mul_f32_e32 v114, 0xbfb8aa3b, v114
	v_add_f32_e32 v113, 1.0, v117
	v_add_f32_e32 v117, 1.0, v147
	v_exp_f32_e32 v118, v118
	v_exp_f32_e32 v147, v114
	v_rcp_f32_e32 v178, v124
	v_add_f32_e32 v123, 1.0, v125
	v_add_f32_e32 v124, 1.0, v126
	v_mul_f32_e32 v119, 0xbfb8aa3b, v119
	v_mul_f32_e32 v115, 0xbfb8aa3b, v115
	v_rcp_f32_e32 v122, v122
	v_rcp_f32_e32 v123, v123
	v_rcp_f32_e32 v179, v124
	v_add_f32_e32 v114, 1.0, v118
	v_add_f32_e32 v118, 1.0, v147
	v_exp_f32_e32 v119, v119
	v_exp_f32_e32 v147, v115
	v_rcp_f32_e32 v112, v112
	v_rcp_f32_e32 v113, v113
	v_add_f32_e32 v115, 1.0, v119
	v_add_f32_e32 v119, 1.0, v147
	v_rcp_f32_e32 v120, v120
	v_rcp_f32_e32 v121, v121
	v_rcp_f32_e32 v116, v116
	v_rcp_f32_e32 v117, v117
	v_rcp_f32_e32 v114, v114
	v_rcp_f32_e32 v118, v118
	v_rcp_f32_e32 v115, v115
	v_rcp_f32_e32 v119, v119
	v_pk_add_f32 v[92:93], v[92:93], v[132:133]
	v_pk_add_f32 v[80:81], v[80:81], v[128:129]
	v_mul_f32_e32 v92, 0xbfb8aa3b, v92
	v_mul_f32_e32 v80, 0xbfb8aa3b, v80
	v_exp_f32_e32 v92, v92
	v_exp_f32_e32 v147, v80
	v_mul_f32_e32 v93, 0xbfb8aa3b, v93
	v_mul_f32_e32 v81, 0xbfb8aa3b, v81
	v_add_f32_e32 v80, 1.0, v92
	v_add_f32_e32 v92, 1.0, v147
	v_exp_f32_e32 v93, v93
	v_exp_f32_e32 v147, v81
	v_pk_add_f32 v[76:77], v[76:77], v[140:141]
	v_pk_add_f32 v[72:73], v[72:73], v[136:137]
	v_pk_add_f32 v[94:95], v[94:95], v[134:135]
	s_waitcnt vmcnt(3)
;     __device__ __forceinline__ void fused(f32x4 (&acc)[2][2][4][2], const Unit& u, int wr, int wc, int fr, int fq, PG8_LAS unsigned char* lds, int wid, int lane) const {
;     ...
;         for (int ai = 0; ai < 2; ++ai)
; #pragma unroll
;             for (int m = 0; m < 4; ++m) { const size_t off = (size_t)(u.pm * BM + ai * HALF + wr * 64 + m * 16 + fr) * 1024 + col0;
; #pragma unroll
;                 for (int bj = 0; bj < 2; ++bj) {
;                     const u32x4 xw = *(const u32x4*)(x1b + off + bj * HALF);
;                     f32x4 x0, x1;
;                     x0[0] = __uint_as_float(xw.x << 16); x0[1] = __uint_as_float(xw.x & 0xffff0000u); x0[2] = __uint_as_float(xw.y << 16); x0[3] = __uint_as_float(xw.y & 0xffff0000u);
;                     x1[0] = __uint_as_float(xw.z << 16); x1[1] = __uint_as_float(xw.z & 0xffff0000u); x1[2] = __uint_as_float(xw.w << 16); x1[3] = __uint_as_float(xw.w & 0xffff0000u);
;                     const u32x4 pw = *(const u32x4*)(pp + off + bj * HALF);
;                     f32x4 p0, p1;
;                     p0[0] = __uint_as_float(pw.x << 16); p0[1] = __uint_as_float(pw.x & 0xffff0000u); p0[2] = __uint_as_float(pw.y << 16); p0[3] = __uint_as_float(pw.y & 0xffff0000u);
;                     p1[0] = __uint_as_float(pw.z << 16); p1[1] = __uint_as_float(pw.z & 0xffff0000u); p1[2] = __uint_as_float(pw.w << 16); p1[3] = __uint_as_float(pw.w & 0xffff0000u);
;                     f32x4 g0 = acc[ai][bj][m][0], g1 = acc[ai][bj][m][1];
; #pragma unroll
;                     for (int e = 0; e < 4; ++e) { g0[e] = __builtin_amdgcn_rcpf(1.f + __expf(-g0[e])); g1[e] = __builtin_amdgcn_rcpf(1.f + __expf(-g1[e])); }
;                     acc[ai][bj][m][0] = x0 + g0 * p0; acc[ai][bj][m][1] = x1 + g1 * p1; }
	v_lshlrev_b32_e32 v168, 16, v152
	v_and_b32_e32 v169, 0xffff0000, v152
	v_lshlrev_b32_e32 v152, 16, v153
	v_and_b32_e32 v153, 0xffff0000, v153
	v_lshlrev_b32_e32 v170, 16, v154
	v_and_b32_e32 v171, 0xffff0000, v154
	v_lshlrev_b32_e32 v154, 16, v155
	v_and_b32_e32 v155, 0xffff0000, v155
	s_waitcnt vmcnt(2)
	v_lshlrev_b32_e32 v172, 16, v156
	v_and_b32_e32 v173, 0xffff0000, v156
	v_lshlrev_b32_e32 v156, 16, v157
	v_and_b32_e32 v157, 0xffff0000, v157
	v_lshlrev_b32_e32 v174, 16, v158
	v_and_b32_e32 v175, 0xffff0000, v158
	v_lshlrev_b32_e32 v158, 16, v159
	v_and_b32_e32 v159, 0xffff0000, v159
	v_pk_fma_f32 v[126:127], v[122:123], v[156:157], v[152:153]
	v_pk_fma_f32 v[122:123], v[178:179], v[158:159], v[154:155]
	s_waitcnt vmcnt(1)
	v_lshlrev_b32_e32 v152, 16, v160
	v_and_b32_e32 v153, 0xffff0000, v160
	v_lshlrev_b32_e32 v154, 16, v161
	v_and_b32_e32 v155, 0xffff0000, v161
	s_waitcnt vmcnt(0)
	v_lshlrev_b32_e32 v160, 16, v164
	v_and_b32_e32 v161, 0xffff0000, v164
	v_pk_fma_f32 v[112:113], v[112:113], v[160:161], v[152:153]
	v_add_u32_e32 v152, 0x80, v146
	v_ashrrev_i32_e32 v153, 31, v152
	v_lshlrev_b64 v[152:153], 10, v[152:153]
	v_lshlrev_b32_e32 v156, 16, v162
	v_and_b32_e32 v157, 0xffff0000, v162
	v_lshlrev_b32_e32 v158, 16, v163
	v_and_b32_e32 v159, 0xffff0000, v163
	v_lshlrev_b32_e32 v162, 16, v165
	v_and_b32_e32 v163, 0xffff0000, v165
	v_lshlrev_b32_e32 v164, 16, v166
	v_and_b32_e32 v165, 0xffff0000, v166
	v_lshlrev_b32_e32 v166, 16, v167
	v_and_b32_e32 v167, 0xffff0000, v167
	v_lshl_add_u64 v[152:153], v[152:153], 0, v[144:145]
	v_pk_fma_f32 v[124:125], v[120:121], v[172:173], v[168:169]
	v_pk_fma_f32 v[120:121], v[176:177], v[174:175], v[170:171]
	v_pk_fma_f32 v[114:115], v[114:115], v[162:163], v[154:155]
	v_pk_fma_f32 v[116:117], v[116:117], v[164:165], v[156:157]
	v_pk_fma_f32 v[118:119], v[118:119], v[166:167], v[158:159]
	v_lshlrev_b64 v[156:157], 1, v[152:153]
	v_lshl_add_u64 v[160:161], s[8:9], 0, v[156:157]
	global_load_dwordx4 v[152:155], v[160:161], off
	v_lshl_add_u64 v[164:165], s[0:1], 0, v[156:157]
	global_load_dwordx4 v[156:159], v[164:165], off
	s_nop 0
	global_load_dwordx4 v[160:163], v[160:161], off offset:256
	s_nop 0
	global_load_dwordx4 v[164:167], v[164:165], off offset:256
	v_mul_f32_e32 v76, 0xbfb8aa3b, v76
	v_mul_f32_e32 v72, 0xbfb8aa3b, v72
	v_pk_add_f32 v[82:83], v[82:83], v[130:131]
	v_rcp_f32_e32 v176, v92
	v_add_f32_e32 v81, 1.0, v93
	v_add_f32_e32 v92, 1.0, v147
	v_mul_f32_e32 v93, 0xbfb8aa3b, v94
	v_exp_f32_e32 v76, v76
	v_exp_f32_e32 v147, v72
	v_exp_f32_e32 v93, v93
	v_mul_f32_e32 v82, 0xbfb8aa3b, v82
	v_exp_f32_e32 v94, v82
	v_mul_f32_e32 v77, 0xbfb8aa3b, v77
	v_mul_f32_e32 v73, 0xbfb8aa3b, v73
	v_add_f32_e32 v72, 1.0, v76
	v_add_f32_e32 v76, 1.0, v147
	v_exp_f32_e32 v77, v77
	v_exp_f32_e32 v147, v73
	v_add_f32_e32 v82, 1.0, v93
	v_mul_f32_e32 v93, 0xbfb8aa3b, v95
	v_mul_f32_e32 v83, 0xbfb8aa3b, v83
	v_pk_add_f32 v[78:79], v[78:79], v[142:143]
	v_pk_add_f32 v[74:75], v[74:75], v[138:139]
	v_rcp_f32_e32 v177, v92
	v_add_f32_e32 v92, 1.0, v94
	v_exp_f32_e32 v93, v93
	v_exp_f32_e32 v94, v83
	v_mul_f32_e32 v78, 0xbfb8aa3b, v78
	v_mul_f32_e32 v74, 0xbfb8aa3b, v74
	v_add_f32_e32 v73, 1.0, v77
	v_add_f32_e32 v77, 1.0, v147
	v_exp_f32_e32 v78, v78
	v_exp_f32_e32 v147, v74
	v_rcp_f32_e32 v178, v92
	v_add_f32_e32 v83, 1.0, v93
	v_add_f32_e32 v92, 1.0, v94
	v_rcp_f32_e32 v82, v82
	v_rcp_f32_e32 v83, v83
	v_rcp_f32_e32 v179, v92
	v_mul_f32_e32 v79, 0xbfb8aa3b, v79
	v_mul_f32_e32 v75, 0xbfb8aa3b, v75
	v_rcp_f32_e32 v72, v72
	v_rcp_f32_e32 v73, v73
	v_add_f32_e32 v74, 1.0, v78
	v_add_f32_e32 v78, 1.0, v147
	v_exp_f32_e32 v79, v79
	v_exp_f32_e32 v147, v75
	v_rcp_f32_e32 v76, v76
	v_rcp_f32_e32 v77, v77
	v_add_f32_e32 v75, 1.0, v79
	v_add_f32_e32 v79, 1.0, v147
	v_rcp_f32_e32 v80, v80
	v_rcp_f32_e32 v81, v81
	v_rcp_f32_e32 v74, v74
	v_rcp_f32_e32 v78, v78
	v_rcp_f32_e32 v75, v75
	v_rcp_f32_e32 v79, v79
	v_pk_add_f32 v[52:53], v[52:53], v[132:133]
	v_pk_add_f32 v[48:49], v[48:49], v[128:129]
	v_mul_f32_e32 v52, 0xbfb8aa3b, v52
	v_mul_f32_e32 v48, 0xbfb8aa3b, v48
	v_exp_f32_e32 v52, v52
	v_exp_f32_e32 v147, v48
	v_mul_f32_e32 v53, 0xbfb8aa3b, v53
	v_mul_f32_e32 v49, 0xbfb8aa3b, v49
	v_add_f32_e32 v48, 1.0, v52
	v_add_f32_e32 v52, 1.0, v147
	v_exp_f32_e32 v53, v53
	v_exp_f32_e32 v147, v49
	v_pk_add_f32 v[44:45], v[44:45], v[140:141]
	v_pk_add_f32 v[40:41], v[40:41], v[136:137]
	v_pk_add_f32 v[54:55], v[54:55], v[134:135]
	v_mul_f32_e32 v44, 0xbfb8aa3b, v44
	v_mul_f32_e32 v40, 0xbfb8aa3b, v40
	v_pk_add_f32 v[50:51], v[50:51], v[130:131]
	v_add_f32_e32 v49, 1.0, v53
	v_mul_f32_e32 v53, 0xbfb8aa3b, v54
	s_waitcnt vmcnt(3)
	v_lshlrev_b32_e32 v168, 16, v152
	v_and_b32_e32 v169, 0xffff0000, v152
	v_lshlrev_b32_e32 v152, 16, v153
	v_and_b32_e32 v153, 0xffff0000, v153
	v_lshlrev_b32_e32 v170, 16, v154
	v_and_b32_e32 v171, 0xffff0000, v154
	v_lshlrev_b32_e32 v154, 16, v155
	v_and_b32_e32 v155, 0xffff0000, v155
	s_waitcnt vmcnt(2)
	v_lshlrev_b32_e32 v172, 16, v156
	v_and_b32_e32 v173, 0xffff0000, v156
	v_lshlrev_b32_e32 v156, 16, v157
	v_and_b32_e32 v157, 0xffff0000, v157
	v_lshlrev_b32_e32 v174, 16, v158
	v_and_b32_e32 v175, 0xffff0000, v158
	v_lshlrev_b32_e32 v158, 16, v159
	v_and_b32_e32 v159, 0xffff0000, v159
	v_pk_fma_f32 v[94:95], v[82:83], v[156:157], v[152:153]
	v_pk_fma_f32 v[82:83], v[178:179], v[158:159], v[154:155]
	s_waitcnt vmcnt(1)
	v_lshlrev_b32_e32 v152, 16, v160
	v_and_b32_e32 v153, 0xffff0000, v160
	v_lshlrev_b32_e32 v154, 16, v161
	v_and_b32_e32 v155, 0xffff0000, v161
	s_waitcnt vmcnt(0)
;     __device__ __forceinline__ void fused(f32x4 (&acc)[2][2][4][2], const Unit& u, int wr, int wc, int fr, int fq, PG8_LAS unsigned char* lds, int wid, int lane) const {
;     ...
; #pragma unroll
;         for (int bj = 0; bj < 2; ++bj) {
;             const f32x4 b0 = *(const f32x4*)(gb + col0 + bj * HALF), b1 = *(const f32x4*)(gb + col0 + bj * HALF + 4);
; #pragma unroll
;             for (int ai = 0; ai < 2; ++ai)
; #pragma unroll
;                 for (int m = 0; m < 4; ++m) { acc[ai][bj][m][0] += b0; acc[ai][bj][m][1] += b1; } }
; #pragma unroll
;         for (int ai = 0; ai < 2; ++ai)
; #pragma unroll
;             for (int m = 0; m < 4; ++m) { const size_t off = (size_t)(u.pm * BM + ai * HALF + wr * 64 + m * 16 + fr) * 1024 + col0;
; #pragma unroll
;                 for (int bj = 0; bj < 2; ++bj) {
;                     const u32x4 xw = *(const u32x4*)(x1b + off + bj * HALF);
;                     f32x4 x0, x1;
;                     x0[0] = __uint_as_float(xw.x << 16); x0[1] = __uint_as_float(xw.x & 0xffff0000u); x0[2] = __uint_as_float(xw.y << 16); x0[3] = __uint_as_float(xw.y & 0xffff0000u);
;                     x1[0] = __uint_as_float(xw.z << 16); x1[1] = __uint_as_float(xw.z & 0xffff0000u); x1[2] = __uint_as_float(xw.w << 16); x1[3] = __uint_as_float(xw.w & 0xffff0000u);
;                     const u32x4 pw = *(const u32x4*)(pp + off + bj * HALF);
;                     f32x4 p0, p1;
;                     p0[0] = __uint_as_float(pw.x << 16); p0[1] = __uint_as_float(pw.x & 0xffff0000u); p0[2] = __uint_as_float(pw.y << 16); p0[3] = __uint_as_float(pw.y & 0xffff0000u);
;                     p1[0] = __uint_as_float(pw.z << 16); p1[1] = __uint_as_float(pw.z & 0xffff0000u); p1[2] = __uint_as_float(pw.w << 16); p1[3] = __uint_as_float(pw.w & 0xffff0000u);
;                     f32x4 g0 = acc[ai][bj][m][0], g1 = acc[ai][bj][m][1];
; #pragma unroll
;                     for (int e = 0; e < 4; ++e) { g0[e] = __builtin_amdgcn_rcpf(1.f + __expf(-g0[e])); g1[e] = __builtin_amdgcn_rcpf(1.f + __expf(-g1[e])); }
;                     acc[ai][bj][m][0] = x0 + g0 * p0; acc[ai][bj][m][1] = x1 + g1 * p1; }
	v_lshlrev_b32_e32 v160, 16, v164
	v_and_b32_e32 v161, 0xffff0000, v164
	v_pk_fma_f32 v[72:73], v[72:73], v[160:161], v[152:153]
	v_add_u32_e32 v152, 0x90, v146
	v_ashrrev_i32_e32 v153, 31, v152
	v_lshlrev_b64 v[152:153], 10, v[152:153]
	v_lshlrev_b32_e32 v156, 16, v162
	v_and_b32_e32 v157, 0xffff0000, v162
	v_lshlrev_b32_e32 v158, 16, v163
	v_and_b32_e32 v159, 0xffff0000, v163
	v_lshlrev_b32_e32 v162, 16, v165
	v_and_b32_e32 v163, 0xffff0000, v165
	v_lshlrev_b32_e32 v164, 16, v166
	v_and_b32_e32 v165, 0xffff0000, v166
	v_lshl_add_u64 v[152:153], v[152:153], 0, v[144:145]
	v_lshlrev_b32_e32 v166, 16, v167
	v_and_b32_e32 v167, 0xffff0000, v167
	v_pk_fma_f32 v[76:77], v[76:77], v[164:165], v[156:157]
	v_lshlrev_b64 v[156:157], 1, v[152:153]
	v_pk_fma_f32 v[92:93], v[80:81], v[172:173], v[168:169]
	v_pk_fma_f32 v[80:81], v[176:177], v[174:175], v[170:171]
	v_pk_fma_f32 v[74:75], v[74:75], v[162:163], v[154:155]
	v_pk_fma_f32 v[78:79], v[78:79], v[166:167], v[158:159]
	v_lshl_add_u64 v[160:161], s[8:9], 0, v[156:157]
	global_load_dwordx4 v[152:155], v[160:161], off
	v_lshl_add_u64 v[164:165], s[0:1], 0, v[156:157]
	global_load_dwordx4 v[156:159], v[164:165], off
	s_nop 0
	global_load_dwordx4 v[160:163], v[160:161], off offset:256
	s_nop 0
	global_load_dwordx4 v[164:167], v[164:165], off offset:256
	v_rcp_f32_e32 v176, v52
	v_add_f32_e32 v52, 1.0, v147
	v_exp_f32_e32 v44, v44
	v_exp_f32_e32 v147, v40
	v_exp_f32_e32 v53, v53
	v_mul_f32_e32 v50, 0xbfb8aa3b, v50
	v_exp_f32_e32 v54, v50
	v_mul_f32_e32 v45, 0xbfb8aa3b, v45
	v_mul_f32_e32 v41, 0xbfb8aa3b, v41
	v_add_f32_e32 v40, 1.0, v44
	v_add_f32_e32 v44, 1.0, v147
	v_exp_f32_e32 v45, v45
	v_exp_f32_e32 v147, v41
	v_add_f32_e32 v50, 1.0, v53
	v_mul_f32_e32 v53, 0xbfb8aa3b, v55
	v_mul_f32_e32 v51, 0xbfb8aa3b, v51
	v_pk_add_f32 v[46:47], v[46:47], v[142:143]
	v_pk_add_f32 v[42:43], v[42:43], v[138:139]
	v_rcp_f32_e32 v177, v52
	v_add_f32_e32 v52, 1.0, v54
	v_exp_f32_e32 v53, v53
	v_exp_f32_e32 v54, v51
	v_mul_f32_e32 v46, 0xbfb8aa3b, v46
	v_mul_f32_e32 v42, 0xbfb8aa3b, v42
	v_add_f32_e32 v41, 1.0, v45
	v_add_f32_e32 v45, 1.0, v147
	v_exp_f32_e32 v46, v46
	v_exp_f32_e32 v147, v42
	v_rcp_f32_e32 v178, v52
	v_add_f32_e32 v51, 1.0, v53
	v_add_f32_e32 v52, 1.0, v54
	v_rcp_f32_e32 v50, v50
	v_rcp_f32_e32 v51, v51
	v_rcp_f32_e32 v179, v52
	v_mul_f32_e32 v47, 0xbfb8aa3b, v47
	v_mul_f32_e32 v43, 0xbfb8aa3b, v43
	v_rcp_f32_e32 v40, v40
	v_rcp_f32_e32 v41, v41
	v_add_f32_e32 v42, 1.0, v46
	v_add_f32_e32 v46, 1.0, v147
	v_exp_f32_e32 v47, v47
	v_exp_f32_e32 v147, v43
	v_rcp_f32_e32 v44, v44
	v_rcp_f32_e32 v45, v45
	v_add_f32_e32 v43, 1.0, v47
	v_add_f32_e32 v47, 1.0, v147
	v_rcp_f32_e32 v48, v48
	v_rcp_f32_e32 v49, v49
	v_rcp_f32_e32 v42, v42
	v_rcp_f32_e32 v46, v46
	v_rcp_f32_e32 v43, v43
	v_rcp_f32_e32 v47, v47
	v_pk_add_f32 v[28:29], v[28:29], v[132:133]
	v_pk_add_f32 v[24:25], v[24:25], v[128:129]
	v_mul_f32_e32 v28, 0xbfb8aa3b, v28
	v_mul_f32_e32 v24, 0xbfb8aa3b, v24
	v_exp_f32_e32 v28, v28
	v_exp_f32_e32 v147, v24
	v_mul_f32_e32 v25, 0xbfb8aa3b, v25
	v_pk_add_f32 v[20:21], v[20:21], v[140:141]
	v_add_f32_e32 v24, 1.0, v28
	v_add_f32_e32 v28, 1.0, v147
	v_exp_f32_e32 v147, v25
	v_pk_add_f32 v[16:17], v[16:17], v[136:137]
	v_mul_f32_e32 v20, 0xbfb8aa3b, v20
	v_mul_f32_e32 v16, 0xbfb8aa3b, v16
	v_mul_f32_e32 v29, 0xbfb8aa3b, v29
	v_exp_f32_e32 v20, v20
	v_exp_f32_e32 v29, v29
	v_mul_f32_e32 v21, 0xbfb8aa3b, v21
	v_mul_f32_e32 v17, 0xbfb8aa3b, v17
	v_pk_add_f32 v[30:31], v[30:31], v[134:135]
	v_exp_f32_e32 v21, v21
	v_pk_add_f32 v[26:27], v[26:27], v[130:131]
	v_add_f32_e32 v25, 1.0, v29
	v_mul_f32_e32 v29, 0xbfb8aa3b, v30
	v_pk_add_f32 v[22:23], v[22:23], v[142:143]
	s_waitcnt vmcnt(3)
	v_lshlrev_b32_e32 v168, 16, v152
	v_and_b32_e32 v169, 0xffff0000, v152
	v_lshlrev_b32_e32 v152, 16, v153
	v_and_b32_e32 v153, 0xffff0000, v153
	v_lshlrev_b32_e32 v170, 16, v154
	v_and_b32_e32 v171, 0xffff0000, v154
	v_lshlrev_b32_e32 v154, 16, v155
	v_and_b32_e32 v155, 0xffff0000, v155
	s_waitcnt vmcnt(2)
	v_lshlrev_b32_e32 v172, 16, v156
	v_and_b32_e32 v173, 0xffff0000, v156
	v_lshlrev_b32_e32 v156, 16, v157
	v_and_b32_e32 v157, 0xffff0000, v157
	v_lshlrev_b32_e32 v174, 16, v158
	v_and_b32_e32 v175, 0xffff0000, v158
	v_lshlrev_b32_e32 v158, 16, v159
	v_and_b32_e32 v159, 0xffff0000, v159
	v_pk_fma_f32 v[54:55], v[50:51], v[156:157], v[152:153]
	v_pk_fma_f32 v[50:51], v[178:179], v[158:159], v[154:155]
	s_waitcnt vmcnt(1)
	v_lshlrev_b32_e32 v152, 16, v160
	v_and_b32_e32 v153, 0xffff0000, v160
	v_lshlrev_b32_e32 v154, 16, v161
	v_and_b32_e32 v155, 0xffff0000, v161
	s_waitcnt vmcnt(0)
;     __device__ __forceinline__ void fused(f32x4 (&acc)[2][2][4][2], const Unit& u, int wr, int wc, int fr, int fq, PG8_LAS unsigned char* lds, int wid, int lane) const {
;     ...
; #pragma unroll
;         for (int bj = 0; bj < 2; ++bj) {
;             const f32x4 b0 = *(const f32x4*)(gb + col0 + bj * HALF), b1 = *(const f32x4*)(gb + col0 + bj * HALF + 4);
; #pragma unroll
;             for (int ai = 0; ai < 2; ++ai)
; #pragma unroll
;                 for (int m = 0; m < 4; ++m) { acc[ai][bj][m][0] += b0; acc[ai][bj][m][1] += b1; } }
; #pragma unroll
;         for (int ai = 0; ai < 2; ++ai)
; #pragma unroll
;             for (int m = 0; m < 4; ++m) { const size_t off = (size_t)(u.pm * BM + ai * HALF + wr * 64 + m * 16 + fr) * 1024 + col0;
; #pragma unroll
;                 for (int bj = 0; bj < 2; ++bj) {
;                     const u32x4 xw = *(const u32x4*)(x1b + off + bj * HALF);
;                     f32x4 x0, x1;
;                     x0[0] = __uint_as_float(xw.x << 16); x0[1] = __uint_as_float(xw.x & 0xffff0000u); x0[2] = __uint_as_float(xw.y << 16); x0[3] = __uint_as_float(xw.y & 0xffff0000u);
;                     x1[0] = __uint_as_float(xw.z << 16); x1[1] = __uint_as_float(xw.z & 0xffff0000u); x1[2] = __uint_as_float(xw.w << 16); x1[3] = __uint_as_float(xw.w & 0xffff0000u);
;                     const u32x4 pw = *(const u32x4*)(pp + off + bj * HALF);
;                     f32x4 p0, p1;
;                     p0[0] = __uint_as_float(pw.x << 16); p0[1] = __uint_as_float(pw.x & 0xffff0000u); p0[2] = __uint_as_float(pw.y << 16); p0[3] = __uint_as_float(pw.y & 0xffff0000u);
;                     p1[0] = __uint_as_float(pw.z << 16); p1[1] = __uint_as_float(pw.z & 0xffff0000u); p1[2] = __uint_as_float(pw.w << 16); p1[3] = __uint_as_float(pw.w & 0xffff0000u);
;                     f32x4 g0 = acc[ai][bj][m][0], g1 = acc[ai][bj][m][1];
; #pragma unroll
;                     for (int e = 0; e < 4; ++e) { g0[e] = __builtin_amdgcn_rcpf(1.f + __expf(-g0[e])); g1[e] = __builtin_amdgcn_rcpf(1.f + __expf(-g1[e])); }
;                     acc[ai][bj][m][0] = x0 + g0 * p0; acc[ai][bj][m][1] = x1 + g1 * p1; }
	v_lshlrev_b32_e32 v160, 16, v164
	v_and_b32_e32 v161, 0xffff0000, v164
	v_pk_fma_f32 v[40:41], v[40:41], v[160:161], v[152:153]
	v_add_u32_e32 v152, 0xa0, v146
	v_ashrrev_i32_e32 v153, 31, v152
	v_lshlrev_b64 v[152:153], 10, v[152:153]
	v_lshlrev_b32_e32 v156, 16, v162
	v_and_b32_e32 v157, 0xffff0000, v162
	v_lshlrev_b32_e32 v158, 16, v163
	v_and_b32_e32 v159, 0xffff0000, v163
	v_lshlrev_b32_e32 v162, 16, v165
	v_and_b32_e32 v163, 0xffff0000, v165
	v_lshlrev_b32_e32 v164, 16, v166
	v_and_b32_e32 v165, 0xffff0000, v166
	v_lshl_add_u64 v[152:153], v[152:153], 0, v[144:145]
	v_lshlrev_b32_e32 v166, 16, v167
	v_and_b32_e32 v167, 0xffff0000, v167
	v_pk_fma_f32 v[44:45], v[44:45], v[164:165], v[156:157]
	v_lshlrev_b64 v[156:157], 1, v[152:153]
	v_pk_fma_f32 v[52:53], v[48:49], v[172:173], v[168:169]
	v_pk_fma_f32 v[48:49], v[176:177], v[174:175], v[170:171]
	v_pk_fma_f32 v[42:43], v[42:43], v[162:163], v[154:155]
	v_pk_fma_f32 v[46:47], v[46:47], v[166:167], v[158:159]
	v_lshl_add_u64 v[160:161], s[8:9], 0, v[156:157]
	global_load_dwordx4 v[152:155], v[160:161], off
	v_lshl_add_u64 v[164:165], s[0:1], 0, v[156:157]
	global_load_dwordx4 v[156:159], v[164:165], off
	s_nop 0
	global_load_dwordx4 v[160:163], v[160:161], off offset:256
	s_nop 0
	global_load_dwordx4 v[164:167], v[164:165], off offset:256
	v_rcp_f32_e32 v176, v28
	v_add_f32_e32 v28, 1.0, v147
	v_exp_f32_e32 v147, v16
	v_add_f32_e32 v16, 1.0, v20
	v_pk_add_f32 v[18:19], v[18:19], v[138:139]
	v_exp_f32_e32 v29, v29
	v_add_f32_e32 v20, 1.0, v147
	v_exp_f32_e32 v147, v17
	v_mul_f32_e32 v26, 0xbfb8aa3b, v26
	v_exp_f32_e32 v30, v26
	v_mul_f32_e32 v22, 0xbfb8aa3b, v22
	v_mul_f32_e32 v18, 0xbfb8aa3b, v18
	v_add_f32_e32 v17, 1.0, v21
	v_add_f32_e32 v21, 1.0, v147
	v_exp_f32_e32 v22, v22
	v_exp_f32_e32 v147, v18
	v_add_f32_e32 v26, 1.0, v29
	v_mul_f32_e32 v29, 0xbfb8aa3b, v31
	v_mul_f32_e32 v27, 0xbfb8aa3b, v27
	v_rcp_f32_e32 v177, v28
	v_add_f32_e32 v28, 1.0, v30
	v_exp_f32_e32 v29, v29
	v_exp_f32_e32 v30, v27
	v_mul_f32_e32 v23, 0xbfb8aa3b, v23
	v_mul_f32_e32 v19, 0xbfb8aa3b, v19
	v_add_f32_e32 v18, 1.0, v22
	v_add_f32_e32 v22, 1.0, v147
	v_exp_f32_e32 v23, v23
	v_exp_f32_e32 v147, v19
	v_rcp_f32_e32 v178, v28
	v_add_f32_e32 v27, 1.0, v29
	v_add_f32_e32 v28, 1.0, v30
	v_rcp_f32_e32 v26, v26
	v_rcp_f32_e32 v27, v27
	v_rcp_f32_e32 v179, v28
	v_add_f32_e32 v19, 1.0, v23
	v_add_f32_e32 v23, 1.0, v147
	v_add_u32_e32 v146, 0xb0, v146
	v_rcp_f32_e32 v24, v24
	v_rcp_f32_e32 v25, v25
	v_rcp_f32_e32 v16, v16
	v_rcp_f32_e32 v20, v20
	v_rcp_f32_e32 v17, v17
	v_rcp_f32_e32 v21, v21
	v_rcp_f32_e32 v18, v18
	v_rcp_f32_e32 v22, v22
	v_rcp_f32_e32 v19, v19
	v_rcp_f32_e32 v23, v23
	v_ashrrev_i32_e32 v147, 31, v146
	v_lshlrev_b64 v[146:147], 10, v[146:147]
	v_lshl_add_u64 v[146:147], v[146:147], 0, v[144:145]
	v_lshlrev_b64 v[146:147], 1, v[146:147]
	v_pk_add_f32 v[12:13], v[12:13], v[132:133]
	v_pk_add_f32 v[8:9], v[8:9], v[128:129]
	v_mul_f32_e32 v13, 0xbfb8aa3b, v13
	v_exp_f32_e32 v13, v13
	v_mul_f32_e32 v12, 0xbfb8aa3b, v12
	v_mul_f32_e32 v8, 0xbfb8aa3b, v8
	v_pk_add_f32 v[14:15], v[14:15], v[134:135]
	v_pk_add_f32 v[10:11], v[10:11], v[130:131]
	v_exp_f32_e32 v12, v12
	v_mul_f32_e32 v9, 0xbfb8aa3b, v9
	v_mul_f32_e32 v10, 0xbfb8aa3b, v10
	v_mul_f32_e32 v11, 0xbfb8aa3b, v11
	v_pk_add_f32 v[4:5], v[4:5], v[140:141]
	v_pk_add_f32 v[0:1], v[0:1], v[136:137]
	v_mul_f32_e32 v4, 0xbfb8aa3b, v4
	v_mul_f32_e32 v0, 0xbfb8aa3b, v0
	v_exp_f32_e32 v4, v4
	v_mul_f32_e32 v5, 0xbfb8aa3b, v5
	v_mul_f32_e32 v1, 0xbfb8aa3b, v1
	v_exp_f32_e32 v5, v5
	v_pk_add_f32 v[6:7], v[6:7], v[142:143]
	v_pk_add_f32 v[2:3], v[2:3], v[138:139]
	v_mul_f32_e32 v6, 0xbfb8aa3b, v6
	v_mul_f32_e32 v2, 0xbfb8aa3b, v2
	v_exp_f32_e32 v6, v6
	s_waitcnt vmcnt(3)
	v_lshlrev_b32_e32 v168, 16, v152
	v_and_b32_e32 v169, 0xffff0000, v152
	v_lshlrev_b32_e32 v152, 16, v153
	v_and_b32_e32 v153, 0xffff0000, v153
	v_lshlrev_b32_e32 v170, 16, v154
	v_and_b32_e32 v171, 0xffff0000, v154
	v_lshlrev_b32_e32 v154, 16, v155
	v_and_b32_e32 v155, 0xffff0000, v155
	s_waitcnt vmcnt(2)
	v_lshlrev_b32_e32 v172, 16, v156
	v_and_b32_e32 v173, 0xffff0000, v156
	v_lshlrev_b32_e32 v156, 16, v157
	v_and_b32_e32 v157, 0xffff0000, v157
	v_lshlrev_b32_e32 v174, 16, v158
	v_and_b32_e32 v175, 0xffff0000, v158
	v_lshlrev_b32_e32 v158, 16, v159
	v_and_b32_e32 v159, 0xffff0000, v159
	v_pk_fma_f32 v[30:31], v[26:27], v[156:157], v[152:153]
	v_pk_fma_f32 v[26:27], v[178:179], v[158:159], v[154:155]
	s_waitcnt vmcnt(1)
;     __device__ __forceinline__ void fused(f32x4 (&acc)[2][2][4][2], const Unit& u, int wr, int wc, int fr, int fq, PG8_LAS unsigned char* lds, int wid, int lane) const {
;     ...
;         for (int ai = 0; ai < 2; ++ai)
; #pragma unroll
;             for (int m = 0; m < 4; ++m) { const size_t off = (size_t)(u.pm * BM + ai * HALF + wr * 64 + m * 16 + fr) * 1024 + col0;
; #pragma unroll
;                 for (int bj = 0; bj < 2; ++bj) {
;                     const u32x4 xw = *(const u32x4*)(x1b + off + bj * HALF);
;                     f32x4 x0, x1;
;                     x0[0] = __uint_as_float(xw.x << 16); x0[1] = __uint_as_float(xw.x & 0xffff0000u); x0[2] = __uint_as_float(xw.y << 16); x0[3] = __uint_as_float(xw.y & 0xffff0000u);
;                     x1[0] = __uint_as_float(xw.z << 16); x1[1] = __uint_as_float(xw.z & 0xffff0000u); x1[2] = __uint_as_float(xw.w << 16); x1[3] = __uint_as_float(xw.w & 0xffff0000u);
;                     const u32x4 pw = *(const u32x4*)(pp + off + bj * HALF);
;                     f32x4 p0, p1;
;                     p0[0] = __uint_as_float(pw.x << 16); p0[1] = __uint_as_float(pw.x & 0xffff0000u); p0[2] = __uint_as_float(pw.y << 16); p0[3] = __uint_as_float(pw.y & 0xffff0000u);
;                     p1[0] = __uint_as_float(pw.z << 16); p1[1] = __uint_as_float(pw.z & 0xffff0000u); p1[2] = __uint_as_float(pw.w << 16); p1[3] = __uint_as_float(pw.w & 0xffff0000u);
;                     f32x4 g0 = acc[ai][bj][m][0], g1 = acc[ai][bj][m][1];
; #pragma unroll
;                     for (int e = 0; e < 4; ++e) { g0[e] = __builtin_amdgcn_rcpf(1.f + __expf(-g0[e])); g1[e] = __builtin_amdgcn_rcpf(1.f + __expf(-g1[e])); }
;                     acc[ai][bj][m][0] = x0 + g0 * p0; acc[ai][bj][m][1] = x1 + g1 * p1; }
;                 asm volatile("" : "+v"(acc[ai][0][m][0]), "+v"(acc[ai][0][m][1]), "+v"(acc[ai][1][m][0]), "+v"(acc[ai][1][m][1]));
;                 if (m == 3) asm volatile("" ::: "memory"); }
;         if (dry) {
; #pragma unroll
;             for (int ai = 0; ai < 2; ++ai)
; #pragma unroll
;                 for (int m = 0; m < 4; ++m) asm volatile("" :: "v"(acc[ai][0][m][0]), "v"(acc[ai][0][m][1]), "v"(acc[ai][1][m][0]), "v"(acc[ai][1][m][1]));
;             return; }
	v_lshlrev_b32_e32 v152, 16, v160
	v_and_b32_e32 v153, 0xffff0000, v160
	v_lshlrev_b32_e32 v154, 16, v161
	v_and_b32_e32 v155, 0xffff0000, v161
	v_lshlrev_b32_e32 v156, 16, v162
	v_and_b32_e32 v157, 0xffff0000, v162
	v_lshlrev_b32_e32 v158, 16, v163
	v_and_b32_e32 v159, 0xffff0000, v163
	s_waitcnt vmcnt(0)
	v_lshlrev_b32_e32 v160, 16, v164
	v_and_b32_e32 v161, 0xffff0000, v164
	v_lshlrev_b32_e32 v162, 16, v165
	v_and_b32_e32 v163, 0xffff0000, v165
	v_lshlrev_b32_e32 v164, 16, v166
	v_and_b32_e32 v165, 0xffff0000, v166
	v_lshlrev_b32_e32 v166, 16, v167
	v_and_b32_e32 v167, 0xffff0000, v167
	v_pk_fma_f32 v[28:29], v[24:25], v[172:173], v[168:169]
	v_pk_fma_f32 v[24:25], v[176:177], v[174:175], v[170:171]
	v_pk_fma_f32 v[16:17], v[16:17], v[160:161], v[152:153]
	v_pk_fma_f32 v[18:19], v[18:19], v[162:163], v[154:155]
	v_pk_fma_f32 v[20:21], v[20:21], v[164:165], v[156:157]
	v_pk_fma_f32 v[22:23], v[22:23], v[166:167], v[158:159]
	v_lshl_add_u64 v[160:161], s[8:9], 0, v[146:147]
	global_load_dwordx4 v[152:155], v[160:161], off
	v_lshl_add_u64 v[146:147], s[0:1], 0, v[146:147]
	global_load_dwordx4 v[156:159], v[146:147], off
	s_nop 0
	global_load_dwordx4 v[160:163], v[160:161], off offset:256
	s_nop 0
	global_load_dwordx4 v[164:167], v[146:147], off offset:256
	v_exp_f32_e32 v146, v8
	v_exp_f32_e32 v147, v9
	v_add_f32_e32 v9, 1.0, v13
	v_mul_f32_e32 v13, 0xbfb8aa3b, v14
	v_exp_f32_e32 v13, v13
	v_exp_f32_e32 v14, v10
	v_add_f32_e32 v8, 1.0, v12
	v_add_f32_e32 v12, 1.0, v146
	v_rcp_f32_e32 v146, v12
	v_add_f32_e32 v12, 1.0, v147
	v_rcp_f32_e32 v147, v12
	v_add_f32_e32 v10, 1.0, v13
	v_add_f32_e32 v12, 1.0, v14
	v_mul_f32_e32 v13, 0xbfb8aa3b, v15
	v_exp_f32_e32 v14, v11
	v_rcp_f32_e32 v8, v8
	v_rcp_f32_e32 v9, v9
	v_exp_f32_e32 v13, v13
	v_mul_f32_e32 v7, 0xbfb8aa3b, v7
	v_mul_f32_e32 v3, 0xbfb8aa3b, v3
	v_exp_f32_e32 v7, v7
	v_add_f32_e32 v11, 1.0, v13
	v_rcp_f32_e32 v10, v10
	v_rcp_f32_e32 v11, v11
	v_readlane_b32 s0, v252, 18
	v_readlane_b32 s1, v252, 19
	s_andn2_b64 vcc, exec, s[0:1]
	s_mov_b64 s[0:1], -1
	s_waitcnt vmcnt(3)
	v_lshlrev_b32_e32 v128, 16, v152
	v_and_b32_e32 v129, 0xffff0000, v152
	v_lshlrev_b32_e32 v132, 16, v154
	v_and_b32_e32 v133, 0xffff0000, v154
	s_waitcnt vmcnt(2)
	v_lshlrev_b32_e32 v136, 16, v156
	v_and_b32_e32 v137, 0xffff0000, v156
	v_lshlrev_b32_e32 v140, 16, v158
	v_and_b32_e32 v141, 0xffff0000, v158
	v_rcp_f32_e32 v152, v12
	v_add_f32_e32 v12, 1.0, v14
	v_lshlrev_b32_e32 v130, 16, v153
	v_and_b32_e32 v131, 0xffff0000, v153
	v_rcp_f32_e32 v153, v12
	v_pk_fma_f32 v[12:13], v[8:9], v[136:137], v[128:129]
	v_pk_fma_f32 v[8:9], v[146:147], v[140:141], v[132:133]
	v_exp_f32_e32 v146, v0
	v_add_f32_e32 v0, 1.0, v4
	v_rcp_f32_e32 v0, v0
	v_lshlrev_b32_e32 v134, 16, v155
	v_add_f32_e32 v4, 1.0, v146
	v_exp_f32_e32 v146, v1
	v_add_f32_e32 v1, 1.0, v5
	v_rcp_f32_e32 v4, v4
	v_rcp_f32_e32 v1, v1
	v_add_f32_e32 v5, 1.0, v146
	v_exp_f32_e32 v146, v2
	v_add_f32_e32 v2, 1.0, v6
	v_rcp_f32_e32 v5, v5
	v_rcp_f32_e32 v2, v2
	v_add_f32_e32 v6, 1.0, v146
	v_exp_f32_e32 v146, v3
	v_add_f32_e32 v3, 1.0, v7
	v_rcp_f32_e32 v6, v6
	v_rcp_f32_e32 v3, v3
	v_add_f32_e32 v7, 1.0, v146
	v_rcp_f32_e32 v7, v7
	v_and_b32_e32 v135, 0xffff0000, v155
	v_lshlrev_b32_e32 v138, 16, v157
	v_and_b32_e32 v139, 0xffff0000, v157
	v_lshlrev_b32_e32 v142, 16, v159
	v_and_b32_e32 v143, 0xffff0000, v159
	v_pk_fma_f32 v[14:15], v[10:11], v[138:139], v[130:131]
	v_pk_fma_f32 v[10:11], v[152:153], v[142:143], v[134:135]
	s_waitcnt vmcnt(1)
	v_lshlrev_b32_e32 v128, 16, v160
	v_and_b32_e32 v129, 0xffff0000, v160
	v_lshlrev_b32_e32 v130, 16, v161
	v_and_b32_e32 v131, 0xffff0000, v161
	v_lshlrev_b32_e32 v132, 16, v162
	v_and_b32_e32 v133, 0xffff0000, v162
	v_lshlrev_b32_e32 v134, 16, v163
	v_and_b32_e32 v135, 0xffff0000, v163
	s_waitcnt vmcnt(0)
	v_lshlrev_b32_e32 v136, 16, v164
	v_and_b32_e32 v137, 0xffff0000, v164
	v_lshlrev_b32_e32 v138, 16, v165
	v_and_b32_e32 v139, 0xffff0000, v165
	v_lshlrev_b32_e32 v140, 16, v166
	v_and_b32_e32 v141, 0xffff0000, v166
	v_lshlrev_b32_e32 v142, 16, v167
	v_and_b32_e32 v143, 0xffff0000, v167
	v_pk_fma_f32 v[0:1], v[0:1], v[136:137], v[128:129]
	v_pk_fma_f32 v[2:3], v[2:3], v[138:139], v[130:131]
	v_pk_fma_f32 v[4:5], v[4:5], v[140:141], v[132:133]
	v_pk_fma_f32 v[6:7], v[6:7], v[142:143], v[134:135]
	s_nop 0
	s_cbranch_vccnz .LBB0_993
	s_mov_b64 s[0:1], 0
